# speedup vs baseline: 1.0214x; 1.0006x over previous
; __device__ __forceinline__ unsigned cvt_pk_bf16(float lo, float hi) { f32x2 v = {lo, hi}; bf16x2_t b = __builtin_convertvector(v, bf16x2_t); return __builtin_bit_cast(unsigned, b); }
;     __device__ __forceinline__ void operator()(const f32x4 (&acc)[2][2][4][2], const Unit& u, int wr, int wc, int fr, int fq) const {
;         const int row0 = u.pm * BM + wr * 64 + fr, col0 = u.pn * BM + wc * 32 + 8 * fq;
; #pragma unroll
;         for (int ai = 0; ai < 2; ++ai) {
;             u32x4 b[4][2];
; #pragma unroll
;             for (int m = 0; m < 4; ++m)
; #pragma unroll
;                 for (int bj = 0; bj < 2; ++bj) b[m][bj] = *(const u32x4*)(xb + (size_t)(row0 + ai * HALF + m * 16) * ldc + col0 + bj * HALF);
; #pragma unroll
;             for (int m = 0; m < 4; ++m) { const int row = row0 + ai * HALF + m * 16; bf16_t* rowp = xb + (size_t)row * ldc + col0;
;                 float ss = 0.f;
; #pragma unroll
;                 for (int bj = 0; bj < 2; ++bj) { const u32x4 w = b[m][bj];
;                     const f32x4 r0 = {__uint_as_float(w.x << 16), __uint_as_float(w.x & 0xffff0000u), __uint_as_float(w.y << 16), __uint_as_float(w.y & 0xffff0000u)};
;                     const f32x4 r1 = {__uint_as_float(w.z << 16), __uint_as_float(w.z & 0xffff0000u), __uint_as_float(w.w << 16), __uint_as_float(w.w & 0xffff0000u)};
;                     const f32x4 v0 = r0 + acc[ai][bj][m][0], v1 = r1 + acc[ai][bj][m][1];
;                     ss += ((v0[0] * v0[0] + v0[1] * v0[1]) + (v0[2] * v0[2] + v0[3] * v0[3])) + ((v1[0] * v1[0] + v1[1] * v1[1]) + (v1[2] * v1[2] + v1[3] * v1[3]));
;                     u32x4 o; o.x = cvt_pk_bf16(v0[0], v0[1]); o.y = cvt_pk_bf16(v0[2], v0[3]); o.z = cvt_pk_bf16(v1[0], v1[1]); o.w = cvt_pk_bf16(v1[2], v1[3]);
;                     *(u32x4*)(rowp + bj * HALF) = o; }
;                 ss += __shfl_xor(ss, 16); ss += __shfl_xor(ss, 32);
;                 if (fq == 0) rowss[(size_t)row * 32 + u.pn * 4 + wc] = ss; }
.LBB0_419:
	v_lshl_add_u32 v172, s44, 8, v186
	v_lshl_or_b32 v173, s43, 8, v188
	v_lshlrev_b32_e32 v173, 1, v173
	v_lshl_add_u32 v174, v172, 12, v173
	v_lshlrev_b32_e32 v175, 7, v172
	s_lshl_b32 s20, s43, 4
	s_lshl_b32 s21, s35, 2
	s_add_i32 s20, s20, s21
	v_add_u32_e32 v175, s20, v175
	global_load_dwordx4 v[130:133], v174, s[46:47]
	global_load_dwordx4 v[134:137], v174, s[46:47] offset:256
	v_add_u32_e32 v176, 0x10000, v174
	global_load_dwordx4 v[138:141], v176, s[46:47]
	global_load_dwordx4 v[142:145], v176, s[46:47] offset:256
	v_add_u32_e32 v176, 0x20000, v174
	global_load_dwordx4 v[146:149], v176, s[46:47]
	global_load_dwordx4 v[150:153], v176, s[46:47] offset:256
	v_add_u32_e32 v176, 0x30000, v174
	global_load_dwordx4 v[154:157], v176, s[46:47]
	global_load_dwordx4 v[158:161], v176, s[46:47] offset:256
	v_add_u32_e32 v176, 0x80000, v174
	global_load_dwordx4 v[196:199], v176, s[46:47]
	global_load_dwordx4 v[200:203], v176, s[46:47] offset:256
	v_add_u32_e32 v176, 0x90000, v174
	global_load_dwordx4 v[204:207], v176, s[46:47]
	global_load_dwordx4 v[208:211], v176, s[46:47] offset:256
	s_waitcnt vmcnt(10)
	v_lshlrev_b32_e32 v214, 16, v130
	v_and_b32_e32 v215, 0xffff0000, v130
	v_lshlrev_b32_e32 v216, 16, v131
	v_and_b32_e32 v217, 0xffff0000, v131
	v_lshlrev_b32_e32 v179, 16, v132
	v_and_b32_e32 v180, 0xffff0000, v132
	v_lshlrev_b32_e32 v181, 16, v133
	v_and_b32_e32 v182, 0xffff0000, v133
	v_add_f32_e32 v126, v126, v214
	v_add_f32_e32 v127, v127, v215
	v_add_f32_e32 v128, v128, v216
	v_add_f32_e32 v129, v129, v217
	v_add_f32_e32 v122, v122, v179
	v_add_f32_e32 v123, v123, v180
	v_add_f32_e32 v124, v124, v181
	v_add_f32_e32 v125, v125, v182
	v_mul_f32_e32 v214, v127, v127
	v_fmac_f32_e32 v214, v126, v126
	v_mul_f32_e32 v215, v129, v129
	v_fmac_f32_e32 v215, v128, v128
	v_add_f32_e32 v214, v214, v215
	v_mul_f32_e32 v215, v123, v123
	v_fmac_f32_e32 v215, v122, v122
	v_mul_f32_e32 v216, v125, v125
	v_fmac_f32_e32 v216, v124, v124
	v_add_f32_e32 v215, v215, v216
	v_add_f32_e32 v214, v214, v215
	v_mov_b32_e32 v183, v214
	v_cvt_pk_bf16_f32 v126, v126, v127
	v_cvt_pk_bf16_f32 v127, v128, v129
	v_cvt_pk_bf16_f32 v128, v122, v123
	v_cvt_pk_bf16_f32 v129, v124, v125
	v_lshlrev_b32_e32 v214, 16, v134
	v_and_b32_e32 v215, 0xffff0000, v134
	v_lshlrev_b32_e32 v216, 16, v135
	v_and_b32_e32 v217, 0xffff0000, v135
	v_lshlrev_b32_e32 v179, 16, v136
	v_and_b32_e32 v180, 0xffff0000, v136
	v_lshlrev_b32_e32 v181, 16, v137
	v_and_b32_e32 v182, 0xffff0000, v137
	v_add_f32_e32 v118, v118, v214
	v_add_f32_e32 v119, v119, v215
	v_add_f32_e32 v120, v120, v216
	v_add_f32_e32 v121, v121, v217
	v_add_f32_e32 v114, v114, v179
	v_add_f32_e32 v115, v115, v180
	v_add_f32_e32 v116, v116, v181
	v_add_f32_e32 v117, v117, v182
	v_mul_f32_e32 v214, v119, v119
	v_fmac_f32_e32 v214, v118, v118
	v_mul_f32_e32 v215, v121, v121
	v_fmac_f32_e32 v215, v120, v120
	v_add_f32_e32 v214, v214, v215
	v_mul_f32_e32 v215, v115, v115
	v_fmac_f32_e32 v215, v114, v114
	v_mul_f32_e32 v216, v117, v117
	v_fmac_f32_e32 v216, v116, v116
	v_add_f32_e32 v215, v215, v216
	v_add_f32_e32 v214, v214, v215
	v_add_f32_e32 v183, v183, v214
	v_cvt_pk_bf16_f32 v118, v118, v119
	v_cvt_pk_bf16_f32 v119, v120, v121
	v_cvt_pk_bf16_f32 v120, v114, v115
	v_cvt_pk_bf16_f32 v121, v116, v117
	v_add_u32_e32 v176, 0xa0000, v174
	global_load_dwordx4 v[130:133], v176, s[46:47]
	global_load_dwordx4 v[134:137], v176, s[46:47] offset:256
	global_store_dwordx4 v174, v[126:129], s[46:47]
	global_store_dwordx4 v174, v[118:121], s[46:47] offset:256
	v_mov_b32_e32 v217, v183
	s_nop 1
	v_permlane16_swap_b32_e32 v217, v183
	v_add_f32_e32 v183, v183, v217
	v_mov_b32_e32 v217, v183
	s_nop 1
	v_permlane32_swap_b32_e32 v217, v183
	v_add_f32_e32 v183, v183, v217
	s_and_saveexec_b64 s[22:23], s[6:7]
	global_store_dword v175, v183, s[38:39]
	s_or_b64 exec, exec, s[22:23]
	s_waitcnt vmcnt(13)
	v_add_u32_e32 v177, 0x10000, v174
	v_add_u32_e32 v178, 0x800, v175
	v_lshlrev_b32_e32 v214, 16, v138
	v_and_b32_e32 v215, 0xffff0000, v138
	v_lshlrev_b32_e32 v216, 16, v139
	v_and_b32_e32 v217, 0xffff0000, v139
	v_lshlrev_b32_e32 v179, 16, v140
	v_and_b32_e32 v180, 0xffff0000, v140
	v_lshlrev_b32_e32 v181, 16, v141
	v_and_b32_e32 v182, 0xffff0000, v141
	v_add_f32_e32 v110, v110, v214
	v_add_f32_e32 v111, v111, v215
	v_add_f32_e32 v112, v112, v216
	v_add_f32_e32 v113, v113, v217
	v_add_f32_e32 v106, v106, v179
	v_add_f32_e32 v107, v107, v180
	v_add_f32_e32 v108, v108, v181
	v_add_f32_e32 v109, v109, v182
	v_mul_f32_e32 v214, v111, v111
	v_fmac_f32_e32 v214, v110, v110
	v_mul_f32_e32 v215, v113, v113
	v_fmac_f32_e32 v215, v112, v112
	v_add_f32_e32 v214, v214, v215
	v_mul_f32_e32 v215, v107, v107
	v_fmac_f32_e32 v215, v106, v106
	v_mul_f32_e32 v216, v109, v109
	v_fmac_f32_e32 v216, v108, v108
	v_add_f32_e32 v215, v215, v216
	v_add_f32_e32 v214, v214, v215
	v_mov_b32_e32 v183, v214
	v_cvt_pk_bf16_f32 v110, v110, v111
	v_cvt_pk_bf16_f32 v111, v112, v113
	v_cvt_pk_bf16_f32 v112, v106, v107
	v_cvt_pk_bf16_f32 v113, v108, v109
	v_lshlrev_b32_e32 v214, 16, v142
	v_and_b32_e32 v215, 0xffff0000, v142
	v_lshlrev_b32_e32 v216, 16, v143
	v_and_b32_e32 v217, 0xffff0000, v143
	v_lshlrev_b32_e32 v179, 16, v144
	v_and_b32_e32 v180, 0xffff0000, v144
	v_lshlrev_b32_e32 v181, 16, v145
	v_and_b32_e32 v182, 0xffff0000, v145
	v_add_f32_e32 v102, v102, v214
	v_add_f32_e32 v103, v103, v215
	v_add_f32_e32 v104, v104, v216
	v_add_f32_e32 v105, v105, v217
	v_add_f32_e32 v98, v98, v179
	v_add_f32_e32 v99, v99, v180
	v_add_f32_e32 v100, v100, v181
	v_add_f32_e32 v101, v101, v182
	v_mul_f32_e32 v214, v103, v103
	v_fmac_f32_e32 v214, v102, v102
	v_mul_f32_e32 v215, v105, v105
	v_fmac_f32_e32 v215, v104, v104
	v_add_f32_e32 v214, v214, v215
	v_mul_f32_e32 v215, v99, v99
	v_fmac_f32_e32 v215, v98, v98
	v_mul_f32_e32 v216, v101, v101
	v_fmac_f32_e32 v216, v100, v100
	v_add_f32_e32 v215, v215, v216
	v_add_f32_e32 v214, v214, v215
	v_add_f32_e32 v183, v183, v214
	v_cvt_pk_bf16_f32 v102, v102, v103
	v_cvt_pk_bf16_f32 v103, v104, v105
	v_cvt_pk_bf16_f32 v104, v98, v99
	v_cvt_pk_bf16_f32 v105, v100, v101
	v_add_u32_e32 v176, 0xb0000, v174
	global_load_dwordx4 v[138:141], v176, s[46:47]
	global_load_dwordx4 v[142:145], v176, s[46:47] offset:256
	global_store_dwordx4 v177, v[110:113], s[46:47]
	global_store_dwordx4 v177, v[102:105], s[46:47] offset:256
	v_mov_b32_e32 v217, v183
	s_nop 1
	v_permlane16_swap_b32_e32 v217, v183
	v_add_f32_e32 v183, v183, v217
	v_mov_b32_e32 v217, v183
	s_nop 1
	v_permlane32_swap_b32_e32 v217, v183
	v_add_f32_e32 v183, v183, v217
	s_and_saveexec_b64 s[22:23], s[6:7]
	global_store_dword v178, v183, s[38:39]
	s_or_b64 exec, exec, s[22:23]
	s_waitcnt vmcnt(16)
; __device__ __forceinline__ unsigned cvt_pk_bf16(float lo, float hi) { f32x2 v = {lo, hi}; bf16x2_t b = __builtin_convertvector(v, bf16x2_t); return __builtin_bit_cast(unsigned, b); }
;     __device__ __forceinline__ void operator()(const f32x4 (&acc)[2][2][4][2], const Unit& u, int wr, int wc, int fr, int fq) const {
;     ...
;                 for (int bj = 0; bj < 2; ++bj) b[m][bj] = *(const u32x4*)(xb + (size_t)(row0 + ai * HALF + m * 16) * ldc + col0 + bj * HALF);
; #pragma unroll
;             for (int m = 0; m < 4; ++m) { const int row = row0 + ai * HALF + m * 16; bf16_t* rowp = xb + (size_t)row * ldc + col0;
;                 float ss = 0.f;
; #pragma unroll
;                 for (int bj = 0; bj < 2; ++bj) { const u32x4 w = b[m][bj];
;                     const f32x4 r0 = {__uint_as_float(w.x << 16), __uint_as_float(w.x & 0xffff0000u), __uint_as_float(w.y << 16), __uint_as_float(w.y & 0xffff0000u)};
;                     const f32x4 r1 = {__uint_as_float(w.z << 16), __uint_as_float(w.z & 0xffff0000u), __uint_as_float(w.w << 16), __uint_as_float(w.w & 0xffff0000u)};
;                     const f32x4 v0 = r0 + acc[ai][bj][m][0], v1 = r1 + acc[ai][bj][m][1];
;                     ss += ((v0[0] * v0[0] + v0[1] * v0[1]) + (v0[2] * v0[2] + v0[3] * v0[3])) + ((v1[0] * v1[0] + v1[1] * v1[1]) + (v1[2] * v1[2] + v1[3] * v1[3]));
;                     u32x4 o; o.x = cvt_pk_bf16(v0[0], v0[1]); o.y = cvt_pk_bf16(v0[2], v0[3]); o.z = cvt_pk_bf16(v1[0], v1[1]); o.w = cvt_pk_bf16(v1[2], v1[3]);
;                     *(u32x4*)(rowp + bj * HALF) = o; }
;                 ss += __shfl_xor(ss, 16); ss += __shfl_xor(ss, 32);
;                 if (fq == 0) rowss[(size_t)row * 32 + u.pn * 4 + wc] = ss; }
	v_add_u32_e32 v177, 0x20000, v174
	v_add_u32_e32 v178, 0x1000, v175
	v_lshlrev_b32_e32 v214, 16, v146
	v_and_b32_e32 v215, 0xffff0000, v146
	v_lshlrev_b32_e32 v216, 16, v147
	v_and_b32_e32 v217, 0xffff0000, v147
	v_lshlrev_b32_e32 v179, 16, v148
	v_and_b32_e32 v180, 0xffff0000, v148
	v_lshlrev_b32_e32 v181, 16, v149
	v_and_b32_e32 v182, 0xffff0000, v149
	v_add_f32_e32 v94, v94, v214
	v_add_f32_e32 v95, v95, v215
	v_add_f32_e32 v96, v96, v216
	v_add_f32_e32 v97, v97, v217
	v_add_f32_e32 v90, v90, v179
	v_add_f32_e32 v91, v91, v180
	v_add_f32_e32 v92, v92, v181
	v_add_f32_e32 v93, v93, v182
	v_mul_f32_e32 v214, v95, v95
	v_fmac_f32_e32 v214, v94, v94
	v_mul_f32_e32 v215, v97, v97
	v_fmac_f32_e32 v215, v96, v96
	v_add_f32_e32 v214, v214, v215
	v_mul_f32_e32 v215, v91, v91
	v_fmac_f32_e32 v215, v90, v90
	v_mul_f32_e32 v216, v93, v93
	v_fmac_f32_e32 v216, v92, v92
	v_add_f32_e32 v215, v215, v216
	v_add_f32_e32 v214, v214, v215
	v_mov_b32_e32 v183, v214
	v_cvt_pk_bf16_f32 v94, v94, v95
	v_cvt_pk_bf16_f32 v95, v96, v97
	v_cvt_pk_bf16_f32 v96, v90, v91
	v_cvt_pk_bf16_f32 v97, v92, v93
	v_lshlrev_b32_e32 v214, 16, v150
	v_and_b32_e32 v215, 0xffff0000, v150
	v_lshlrev_b32_e32 v216, 16, v151
	v_and_b32_e32 v217, 0xffff0000, v151
	v_lshlrev_b32_e32 v179, 16, v152
	v_and_b32_e32 v180, 0xffff0000, v152
	v_lshlrev_b32_e32 v181, 16, v153
	v_and_b32_e32 v182, 0xffff0000, v153
	v_add_f32_e32 v86, v86, v214
	v_add_f32_e32 v87, v87, v215
	v_add_f32_e32 v88, v88, v216
	v_add_f32_e32 v89, v89, v217
	v_add_f32_e32 v82, v82, v179
	v_add_f32_e32 v83, v83, v180
	v_add_f32_e32 v84, v84, v181
	v_add_f32_e32 v85, v85, v182
	v_mul_f32_e32 v214, v87, v87
	v_fmac_f32_e32 v214, v86, v86
	v_mul_f32_e32 v215, v89, v89
	v_fmac_f32_e32 v215, v88, v88
	v_add_f32_e32 v214, v214, v215
	v_mul_f32_e32 v215, v83, v83
	v_fmac_f32_e32 v215, v82, v82
	v_mul_f32_e32 v216, v85, v85
	v_fmac_f32_e32 v216, v84, v84
	v_add_f32_e32 v215, v215, v216
	v_add_f32_e32 v214, v214, v215
	v_add_f32_e32 v183, v183, v214
	v_cvt_pk_bf16_f32 v86, v86, v87
	v_cvt_pk_bf16_f32 v87, v88, v89
	v_cvt_pk_bf16_f32 v88, v82, v83
	v_cvt_pk_bf16_f32 v89, v84, v85
	global_store_dwordx4 v177, v[94:97], s[46:47]
	global_store_dwordx4 v177, v[86:89], s[46:47] offset:256
	v_mov_b32_e32 v217, v183
	s_nop 1
	v_permlane16_swap_b32_e32 v217, v183
	v_add_f32_e32 v183, v183, v217
	v_mov_b32_e32 v217, v183
	s_nop 1
	v_permlane32_swap_b32_e32 v217, v183
	v_add_f32_e32 v183, v183, v217
	s_and_saveexec_b64 s[22:23], s[6:7]
	global_store_dword v178, v183, s[38:39]
	s_or_b64 exec, exec, s[22:23]
	s_waitcnt vmcnt(17)
	v_add_u32_e32 v177, 0x30000, v174
	v_add_u32_e32 v178, 0x1800, v175
	v_lshlrev_b32_e32 v214, 16, v154
	v_and_b32_e32 v215, 0xffff0000, v154
	v_lshlrev_b32_e32 v216, 16, v155
	v_and_b32_e32 v217, 0xffff0000, v155
	v_lshlrev_b32_e32 v179, 16, v156
	v_and_b32_e32 v180, 0xffff0000, v156
	v_lshlrev_b32_e32 v181, 16, v157
	v_and_b32_e32 v182, 0xffff0000, v157
	v_add_f32_e32 v78, v78, v214
	v_add_f32_e32 v79, v79, v215
	v_add_f32_e32 v80, v80, v216
	v_add_f32_e32 v81, v81, v217
	v_add_f32_e32 v74, v74, v179
	v_add_f32_e32 v75, v75, v180
	v_add_f32_e32 v76, v76, v181
	v_add_f32_e32 v77, v77, v182
	v_mul_f32_e32 v214, v79, v79
	v_fmac_f32_e32 v214, v78, v78
	v_mul_f32_e32 v215, v81, v81
	v_fmac_f32_e32 v215, v80, v80
	v_add_f32_e32 v214, v214, v215
	v_mul_f32_e32 v215, v75, v75
	v_fmac_f32_e32 v215, v74, v74
	v_mul_f32_e32 v216, v77, v77
	v_fmac_f32_e32 v216, v76, v76
	v_add_f32_e32 v215, v215, v216
	v_add_f32_e32 v214, v214, v215
	v_mov_b32_e32 v183, v214
	v_cvt_pk_bf16_f32 v78, v78, v79
	v_cvt_pk_bf16_f32 v79, v80, v81
	v_cvt_pk_bf16_f32 v80, v74, v75
	v_cvt_pk_bf16_f32 v81, v76, v77
	v_lshlrev_b32_e32 v214, 16, v158
	v_and_b32_e32 v215, 0xffff0000, v158
	v_lshlrev_b32_e32 v216, 16, v159
	v_and_b32_e32 v217, 0xffff0000, v159
	v_lshlrev_b32_e32 v179, 16, v160
	v_and_b32_e32 v180, 0xffff0000, v160
	v_lshlrev_b32_e32 v181, 16, v161
	v_and_b32_e32 v182, 0xffff0000, v161
	v_add_f32_e32 v70, v70, v214
	v_add_f32_e32 v71, v71, v215
	v_add_f32_e32 v72, v72, v216
	v_add_f32_e32 v73, v73, v217
	v_add_f32_e32 v66, v66, v179
	v_add_f32_e32 v67, v67, v180
	v_add_f32_e32 v68, v68, v181
	v_add_f32_e32 v69, v69, v182
	v_mul_f32_e32 v214, v71, v71
	v_fmac_f32_e32 v214, v70, v70
	v_mul_f32_e32 v215, v73, v73
	v_fmac_f32_e32 v215, v72, v72
	v_add_f32_e32 v214, v214, v215
	v_mul_f32_e32 v215, v67, v67
	v_fmac_f32_e32 v215, v66, v66
	v_mul_f32_e32 v216, v69, v69
	v_fmac_f32_e32 v216, v68, v68
	v_add_f32_e32 v215, v215, v216
	v_add_f32_e32 v214, v214, v215
	v_add_f32_e32 v183, v183, v214
	v_cvt_pk_bf16_f32 v70, v70, v71
	v_cvt_pk_bf16_f32 v71, v72, v73
	v_cvt_pk_bf16_f32 v72, v66, v67
	v_cvt_pk_bf16_f32 v73, v68, v69
	global_store_dwordx4 v177, v[78:81], s[46:47]
	global_store_dwordx4 v177, v[70:73], s[46:47] offset:256
	v_mov_b32_e32 v217, v183
	s_nop 1
	v_permlane16_swap_b32_e32 v217, v183
	v_add_f32_e32 v183, v183, v217
	v_mov_b32_e32 v217, v183
	s_nop 1
	v_permlane32_swap_b32_e32 v217, v183
	v_add_f32_e32 v183, v183, v217
	s_and_saveexec_b64 s[22:23], s[6:7]
	global_store_dword v178, v183, s[38:39]
	s_or_b64 exec, exec, s[22:23]
	s_waitcnt vmcnt(18)
; __device__ __forceinline__ unsigned cvt_pk_bf16(float lo, float hi) { f32x2 v = {lo, hi}; bf16x2_t b = __builtin_convertvector(v, bf16x2_t); return __builtin_bit_cast(unsigned, b); }
;     __device__ __forceinline__ void operator()(const f32x4 (&acc)[2][2][4][2], const Unit& u, int wr, int wc, int fr, int fq) const {
;     ...
;                 for (int bj = 0; bj < 2; ++bj) b[m][bj] = *(const u32x4*)(xb + (size_t)(row0 + ai * HALF + m * 16) * ldc + col0 + bj * HALF);
; #pragma unroll
;             for (int m = 0; m < 4; ++m) { const int row = row0 + ai * HALF + m * 16; bf16_t* rowp = xb + (size_t)row * ldc + col0;
;                 float ss = 0.f;
; #pragma unroll
;                 for (int bj = 0; bj < 2; ++bj) { const u32x4 w = b[m][bj];
;                     const f32x4 r0 = {__uint_as_float(w.x << 16), __uint_as_float(w.x & 0xffff0000u), __uint_as_float(w.y << 16), __uint_as_float(w.y & 0xffff0000u)};
;                     const f32x4 r1 = {__uint_as_float(w.z << 16), __uint_as_float(w.z & 0xffff0000u), __uint_as_float(w.w << 16), __uint_as_float(w.w & 0xffff0000u)};
;                     const f32x4 v0 = r0 + acc[ai][bj][m][0], v1 = r1 + acc[ai][bj][m][1];
;                     ss += ((v0[0] * v0[0] + v0[1] * v0[1]) + (v0[2] * v0[2] + v0[3] * v0[3])) + ((v1[0] * v1[0] + v1[1] * v1[1]) + (v1[2] * v1[2] + v1[3] * v1[3]));
;                     u32x4 o; o.x = cvt_pk_bf16(v0[0], v0[1]); o.y = cvt_pk_bf16(v0[2], v0[3]); o.z = cvt_pk_bf16(v1[0], v1[1]); o.w = cvt_pk_bf16(v1[2], v1[3]);
;                     *(u32x4*)(rowp + bj * HALF) = o; }
;                 ss += __shfl_xor(ss, 16); ss += __shfl_xor(ss, 32);
;                 if (fq == 0) rowss[(size_t)row * 32 + u.pn * 4 + wc] = ss; }
	v_add_u32_e32 v177, 0x80000, v174
	v_add_u32_e32 v178, 0x4000, v175
	v_lshlrev_b32_e32 v214, 16, v196
	v_and_b32_e32 v215, 0xffff0000, v196
	v_lshlrev_b32_e32 v216, 16, v197
	v_and_b32_e32 v217, 0xffff0000, v197
	v_lshlrev_b32_e32 v179, 16, v198
	v_and_b32_e32 v180, 0xffff0000, v198
	v_lshlrev_b32_e32 v181, 16, v199
	v_and_b32_e32 v182, 0xffff0000, v199
	v_add_f32_e32 v62, v62, v214
	v_add_f32_e32 v63, v63, v215
	v_add_f32_e32 v64, v64, v216
	v_add_f32_e32 v65, v65, v217
	v_add_f32_e32 v58, v58, v179
	v_add_f32_e32 v59, v59, v180
	v_add_f32_e32 v60, v60, v181
	v_add_f32_e32 v61, v61, v182
	v_mul_f32_e32 v214, v63, v63
	v_fmac_f32_e32 v214, v62, v62
	v_mul_f32_e32 v215, v65, v65
	v_fmac_f32_e32 v215, v64, v64
	v_add_f32_e32 v214, v214, v215
	v_mul_f32_e32 v215, v59, v59
	v_fmac_f32_e32 v215, v58, v58
	v_mul_f32_e32 v216, v61, v61
	v_fmac_f32_e32 v216, v60, v60
	v_add_f32_e32 v215, v215, v216
	v_add_f32_e32 v214, v214, v215
	v_mov_b32_e32 v183, v214
	v_cvt_pk_bf16_f32 v62, v62, v63
	v_cvt_pk_bf16_f32 v63, v64, v65
	v_cvt_pk_bf16_f32 v64, v58, v59
	v_cvt_pk_bf16_f32 v65, v60, v61
	v_lshlrev_b32_e32 v214, 16, v200
	v_and_b32_e32 v215, 0xffff0000, v200
	v_lshlrev_b32_e32 v216, 16, v201
	v_and_b32_e32 v217, 0xffff0000, v201
	v_lshlrev_b32_e32 v179, 16, v202
	v_and_b32_e32 v180, 0xffff0000, v202
	v_lshlrev_b32_e32 v181, 16, v203
	v_and_b32_e32 v182, 0xffff0000, v203
	v_add_f32_e32 v54, v54, v214
	v_add_f32_e32 v55, v55, v215
	v_add_f32_e32 v56, v56, v216
	v_add_f32_e32 v57, v57, v217
	v_add_f32_e32 v50, v50, v179
	v_add_f32_e32 v51, v51, v180
	v_add_f32_e32 v52, v52, v181
	v_add_f32_e32 v53, v53, v182
	v_mul_f32_e32 v214, v55, v55
	v_fmac_f32_e32 v214, v54, v54
	v_mul_f32_e32 v215, v57, v57
	v_fmac_f32_e32 v215, v56, v56
	v_add_f32_e32 v214, v214, v215
	v_mul_f32_e32 v215, v51, v51
	v_fmac_f32_e32 v215, v50, v50
	v_mul_f32_e32 v216, v53, v53
	v_fmac_f32_e32 v216, v52, v52
	v_add_f32_e32 v215, v215, v216
	v_add_f32_e32 v214, v214, v215
	v_add_f32_e32 v183, v183, v214
	v_cvt_pk_bf16_f32 v54, v54, v55
	v_cvt_pk_bf16_f32 v55, v56, v57
	v_cvt_pk_bf16_f32 v56, v50, v51
	v_cvt_pk_bf16_f32 v57, v52, v53
	global_store_dwordx4 v177, v[62:65], s[46:47]
	global_store_dwordx4 v177, v[54:57], s[46:47] offset:256
	v_mov_b32_e32 v217, v183
	s_nop 1
	v_permlane16_swap_b32_e32 v217, v183
	v_add_f32_e32 v183, v183, v217
	v_mov_b32_e32 v217, v183
	s_nop 1
	v_permlane32_swap_b32_e32 v217, v183
	v_add_f32_e32 v183, v183, v217
	s_and_saveexec_b64 s[22:23], s[6:7]
	global_store_dword v178, v183, s[38:39]
	s_or_b64 exec, exec, s[22:23]
	s_waitcnt vmcnt(19)
	v_add_u32_e32 v177, 0x90000, v174
	v_add_u32_e32 v178, 0x4800, v175
	v_lshlrev_b32_e32 v214, 16, v204
	v_and_b32_e32 v215, 0xffff0000, v204
	v_lshlrev_b32_e32 v216, 16, v205
	v_and_b32_e32 v217, 0xffff0000, v205
	v_lshlrev_b32_e32 v179, 16, v206
	v_and_b32_e32 v180, 0xffff0000, v206
	v_lshlrev_b32_e32 v181, 16, v207
	v_and_b32_e32 v182, 0xffff0000, v207
	v_add_f32_e32 v46, v46, v214
	v_add_f32_e32 v47, v47, v215
	v_add_f32_e32 v48, v48, v216
	v_add_f32_e32 v49, v49, v217
	v_add_f32_e32 v42, v42, v179
	v_add_f32_e32 v43, v43, v180
	v_add_f32_e32 v44, v44, v181
	v_add_f32_e32 v45, v45, v182
	v_mul_f32_e32 v214, v47, v47
	v_fmac_f32_e32 v214, v46, v46
	v_mul_f32_e32 v215, v49, v49
	v_fmac_f32_e32 v215, v48, v48
	v_add_f32_e32 v214, v214, v215
	v_mul_f32_e32 v215, v43, v43
	v_fmac_f32_e32 v215, v42, v42
	v_mul_f32_e32 v216, v45, v45
	v_fmac_f32_e32 v216, v44, v44
	v_add_f32_e32 v215, v215, v216
	v_add_f32_e32 v214, v214, v215
	v_mov_b32_e32 v183, v214
	v_cvt_pk_bf16_f32 v46, v46, v47
	v_cvt_pk_bf16_f32 v47, v48, v49
	v_cvt_pk_bf16_f32 v48, v42, v43
	v_cvt_pk_bf16_f32 v49, v44, v45
	v_lshlrev_b32_e32 v214, 16, v208
	v_and_b32_e32 v215, 0xffff0000, v208
	v_lshlrev_b32_e32 v216, 16, v209
	v_and_b32_e32 v217, 0xffff0000, v209
	v_lshlrev_b32_e32 v179, 16, v210
	v_and_b32_e32 v180, 0xffff0000, v210
	v_lshlrev_b32_e32 v181, 16, v211
	v_and_b32_e32 v182, 0xffff0000, v211
	v_add_f32_e32 v38, v38, v214
	v_add_f32_e32 v39, v39, v215
	v_add_f32_e32 v40, v40, v216
	v_add_f32_e32 v41, v41, v217
	v_add_f32_e32 v34, v34, v179
	v_add_f32_e32 v35, v35, v180
	v_add_f32_e32 v36, v36, v181
	v_add_f32_e32 v37, v37, v182
	v_mul_f32_e32 v214, v39, v39
	v_fmac_f32_e32 v214, v38, v38
	v_mul_f32_e32 v215, v41, v41
	v_fmac_f32_e32 v215, v40, v40
	v_add_f32_e32 v214, v214, v215
	v_mul_f32_e32 v215, v35, v35
	v_fmac_f32_e32 v215, v34, v34
	v_mul_f32_e32 v216, v37, v37
	v_fmac_f32_e32 v216, v36, v36
	v_add_f32_e32 v215, v215, v216
	v_add_f32_e32 v214, v214, v215
	v_add_f32_e32 v183, v183, v214
	v_cvt_pk_bf16_f32 v38, v38, v39
	v_cvt_pk_bf16_f32 v39, v40, v41
	v_cvt_pk_bf16_f32 v40, v34, v35
	v_cvt_pk_bf16_f32 v41, v36, v37
	global_store_dwordx4 v177, v[46:49], s[46:47]
	global_store_dwordx4 v177, v[38:41], s[46:47] offset:256
	v_mov_b32_e32 v217, v183
	s_nop 1
	v_permlane16_swap_b32_e32 v217, v183
	v_add_f32_e32 v183, v183, v217
	v_mov_b32_e32 v217, v183
	s_nop 1
	v_permlane32_swap_b32_e32 v217, v183
	v_add_f32_e32 v183, v183, v217
	s_and_saveexec_b64 s[22:23], s[6:7]
	global_store_dword v178, v183, s[38:39]
	s_or_b64 exec, exec, s[22:23]
	s_waitcnt vmcnt(20)
; __device__ __forceinline__ unsigned cvt_pk_bf16(float lo, float hi) { f32x2 v = {lo, hi}; bf16x2_t b = __builtin_convertvector(v, bf16x2_t); return __builtin_bit_cast(unsigned, b); }
;     __device__ __forceinline__ void operator()(const f32x4 (&acc)[2][2][4][2], const Unit& u, int wr, int wc, int fr, int fq) const {
;     ...
;                 for (int bj = 0; bj < 2; ++bj) b[m][bj] = *(const u32x4*)(xb + (size_t)(row0 + ai * HALF + m * 16) * ldc + col0 + bj * HALF);
; #pragma unroll
;             for (int m = 0; m < 4; ++m) { const int row = row0 + ai * HALF + m * 16; bf16_t* rowp = xb + (size_t)row * ldc + col0;
;                 float ss = 0.f;
; #pragma unroll
;                 for (int bj = 0; bj < 2; ++bj) { const u32x4 w = b[m][bj];
;                     const f32x4 r0 = {__uint_as_float(w.x << 16), __uint_as_float(w.x & 0xffff0000u), __uint_as_float(w.y << 16), __uint_as_float(w.y & 0xffff0000u)};
;                     const f32x4 r1 = {__uint_as_float(w.z << 16), __uint_as_float(w.z & 0xffff0000u), __uint_as_float(w.w << 16), __uint_as_float(w.w & 0xffff0000u)};
;                     const f32x4 v0 = r0 + acc[ai][bj][m][0], v1 = r1 + acc[ai][bj][m][1];
;                     ss += ((v0[0] * v0[0] + v0[1] * v0[1]) + (v0[2] * v0[2] + v0[3] * v0[3])) + ((v1[0] * v1[0] + v1[1] * v1[1]) + (v1[2] * v1[2] + v1[3] * v1[3]));
;                     u32x4 o; o.x = cvt_pk_bf16(v0[0], v0[1]); o.y = cvt_pk_bf16(v0[2], v0[3]); o.z = cvt_pk_bf16(v1[0], v1[1]); o.w = cvt_pk_bf16(v1[2], v1[3]);
;                     *(u32x4*)(rowp + bj * HALF) = o; }
;                 ss += __shfl_xor(ss, 16); ss += __shfl_xor(ss, 32);
;                 if (fq == 0) rowss[(size_t)row * 32 + u.pn * 4 + wc] = ss; }
	v_add_u32_e32 v177, 0xa0000, v174
	v_add_u32_e32 v178, 0x5000, v175
	v_lshlrev_b32_e32 v214, 16, v130
	v_and_b32_e32 v215, 0xffff0000, v130
	v_lshlrev_b32_e32 v216, 16, v131
	v_and_b32_e32 v217, 0xffff0000, v131
	v_lshlrev_b32_e32 v179, 16, v132
	v_and_b32_e32 v180, 0xffff0000, v132
	v_lshlrev_b32_e32 v181, 16, v133
	v_and_b32_e32 v182, 0xffff0000, v133
	v_add_f32_e32 v30, v30, v214
	v_add_f32_e32 v31, v31, v215
	v_add_f32_e32 v32, v32, v216
	v_add_f32_e32 v33, v33, v217
	v_add_f32_e32 v26, v26, v179
	v_add_f32_e32 v27, v27, v180
	v_add_f32_e32 v28, v28, v181
	v_add_f32_e32 v29, v29, v182
	v_mul_f32_e32 v214, v31, v31
	v_fmac_f32_e32 v214, v30, v30
	v_mul_f32_e32 v215, v33, v33
	v_fmac_f32_e32 v215, v32, v32
	v_add_f32_e32 v214, v214, v215
	v_mul_f32_e32 v215, v27, v27
	v_fmac_f32_e32 v215, v26, v26
	v_mul_f32_e32 v216, v29, v29
	v_fmac_f32_e32 v216, v28, v28
	v_add_f32_e32 v215, v215, v216
	v_add_f32_e32 v214, v214, v215
	v_mov_b32_e32 v183, v214
	v_cvt_pk_bf16_f32 v30, v30, v31
	v_cvt_pk_bf16_f32 v31, v32, v33
	v_cvt_pk_bf16_f32 v32, v26, v27
	v_cvt_pk_bf16_f32 v33, v28, v29
	v_lshlrev_b32_e32 v214, 16, v134
	v_and_b32_e32 v215, 0xffff0000, v134
	v_lshlrev_b32_e32 v216, 16, v135
	v_and_b32_e32 v217, 0xffff0000, v135
	v_lshlrev_b32_e32 v179, 16, v136
	v_and_b32_e32 v180, 0xffff0000, v136
	v_lshlrev_b32_e32 v181, 16, v137
	v_and_b32_e32 v182, 0xffff0000, v137
	v_add_f32_e32 v22, v22, v214
	v_add_f32_e32 v23, v23, v215
	v_add_f32_e32 v24, v24, v216
	v_add_f32_e32 v25, v25, v217
	v_add_f32_e32 v18, v18, v179
	v_add_f32_e32 v19, v19, v180
	v_add_f32_e32 v20, v20, v181
	v_add_f32_e32 v21, v21, v182
	v_mul_f32_e32 v214, v23, v23
	v_fmac_f32_e32 v214, v22, v22
	v_mul_f32_e32 v215, v25, v25
	v_fmac_f32_e32 v215, v24, v24
	v_add_f32_e32 v214, v214, v215
	v_mul_f32_e32 v215, v19, v19
	v_fmac_f32_e32 v215, v18, v18
	v_mul_f32_e32 v216, v21, v21
	v_fmac_f32_e32 v216, v20, v20
	v_add_f32_e32 v215, v215, v216
	v_add_f32_e32 v214, v214, v215
	v_add_f32_e32 v183, v183, v214
	v_cvt_pk_bf16_f32 v22, v22, v23
	v_cvt_pk_bf16_f32 v23, v24, v25
	v_cvt_pk_bf16_f32 v24, v18, v19
	v_cvt_pk_bf16_f32 v25, v20, v21
	global_store_dwordx4 v177, v[30:33], s[46:47]
	global_store_dwordx4 v177, v[22:25], s[46:47] offset:256
	v_mov_b32_e32 v217, v183
	s_nop 1
	v_permlane16_swap_b32_e32 v217, v183
	v_add_f32_e32 v183, v183, v217
	v_mov_b32_e32 v217, v183
	s_nop 1
	v_permlane32_swap_b32_e32 v217, v183
	v_add_f32_e32 v183, v183, v217
	s_and_saveexec_b64 s[22:23], s[6:7]
	global_store_dword v178, v183, s[38:39]
	s_or_b64 exec, exec, s[22:23]
	s_waitcnt vmcnt(18)
	v_add_u32_e32 v177, 0xb0000, v174
	v_add_u32_e32 v178, 0x5800, v175
	v_lshlrev_b32_e32 v214, 16, v138
	v_and_b32_e32 v215, 0xffff0000, v138
	v_lshlrev_b32_e32 v216, 16, v139
	v_and_b32_e32 v217, 0xffff0000, v139
	v_lshlrev_b32_e32 v179, 16, v140
	v_and_b32_e32 v180, 0xffff0000, v140
	v_lshlrev_b32_e32 v181, 16, v141
	v_and_b32_e32 v182, 0xffff0000, v141
	v_add_f32_e32 v14, v14, v214
	v_add_f32_e32 v15, v15, v215
	v_add_f32_e32 v16, v16, v216
	v_add_f32_e32 v17, v17, v217
	v_add_f32_e32 v10, v10, v179
	v_add_f32_e32 v11, v11, v180
	v_add_f32_e32 v12, v12, v181
	v_add_f32_e32 v13, v13, v182
	v_mul_f32_e32 v214, v15, v15
	v_fmac_f32_e32 v214, v14, v14
	v_mul_f32_e32 v215, v17, v17
	v_fmac_f32_e32 v215, v16, v16
	v_add_f32_e32 v214, v214, v215
	v_mul_f32_e32 v215, v11, v11
	v_fmac_f32_e32 v215, v10, v10
	v_mul_f32_e32 v216, v13, v13
	v_fmac_f32_e32 v216, v12, v12
	v_add_f32_e32 v215, v215, v216
	v_add_f32_e32 v214, v214, v215
	v_mov_b32_e32 v183, v214
	v_cvt_pk_bf16_f32 v14, v14, v15
	v_cvt_pk_bf16_f32 v15, v16, v17
	v_cvt_pk_bf16_f32 v16, v10, v11
	v_cvt_pk_bf16_f32 v17, v12, v13
	v_lshlrev_b32_e32 v214, 16, v142
	v_and_b32_e32 v215, 0xffff0000, v142
	v_lshlrev_b32_e32 v216, 16, v143
	v_and_b32_e32 v217, 0xffff0000, v143
	v_lshlrev_b32_e32 v179, 16, v144
	v_and_b32_e32 v180, 0xffff0000, v144
	v_lshlrev_b32_e32 v181, 16, v145
	v_and_b32_e32 v182, 0xffff0000, v145
	v_add_f32_e32 v6, v6, v214
	v_add_f32_e32 v7, v7, v215
	v_add_f32_e32 v8, v8, v216
	v_add_f32_e32 v9, v9, v217
	v_add_f32_e32 v2, v2, v179
	v_add_f32_e32 v3, v3, v180
	v_add_f32_e32 v4, v4, v181
	v_add_f32_e32 v5, v5, v182
	v_mul_f32_e32 v214, v7, v7
	v_fmac_f32_e32 v214, v6, v6
	v_mul_f32_e32 v215, v9, v9
	v_fmac_f32_e32 v215, v8, v8
	v_add_f32_e32 v214, v214, v215
	v_mul_f32_e32 v215, v3, v3
	v_fmac_f32_e32 v215, v2, v2
	v_mul_f32_e32 v216, v5, v5
	v_fmac_f32_e32 v216, v4, v4
	v_add_f32_e32 v215, v215, v216
	v_add_f32_e32 v214, v214, v215
	v_add_f32_e32 v183, v183, v214
	v_cvt_pk_bf16_f32 v6, v6, v7
	v_cvt_pk_bf16_f32 v7, v8, v9
	v_cvt_pk_bf16_f32 v8, v2, v3
	v_cvt_pk_bf16_f32 v9, v4, v5
	global_store_dwordx4 v177, v[14:17], s[46:47]
	global_store_dwordx4 v177, v[6:9], s[46:47] offset:256
	v_mov_b32_e32 v217, v183
	s_nop 1
	v_permlane16_swap_b32_e32 v217, v183
	v_add_f32_e32 v183, v183, v217
	v_mov_b32_e32 v217, v183
	s_nop 1
	v_permlane32_swap_b32_e32 v217, v183
	v_add_f32_e32 v183, v183, v217
	s_and_saveexec_b64 s[22:23], s[6:7]
	global_store_dword v178, v183, s[38:39]
	s_or_b64 exec, exec, s[22:23]
	s_andn2_b64 vcc, exec, s[4:5]
	s_mov_b64 s[4:5], -1
	s_cbranch_vccnz .LBB0_408
	s_andn2_b64 vcc, exec, s[8:9]
	s_cbranch_vccnz .LBB0_407
	s_barrier
	s_branch .LBB0_407

; __device__ __forceinline__ unsigned cvt_pk_bf16(float lo, float hi) { f32x2 v = {lo, hi}; bf16x2_t b = __builtin_convertvector(v, bf16x2_t); return __builtin_bit_cast(unsigned, b); }
;     __device__ __forceinline__ void operator()(const f32x4 (&acc)[2][2][4][2], const Unit& u, int wr, int wc, int fr, int fq) const {
;     ...
; #pragma unroll
;         for (int ai = 0; ai < 2; ++ai) {
;             u32x4 b[4][2];
; #pragma unroll
;             for (int m = 0; m < 4; ++m)
; #pragma unroll
;                 for (int bj = 0; bj < 2; ++bj) b[m][bj] = *(const u32x4*)(xb + (size_t)(row0 + ai * HALF + m * 16) * ldc + col0 + bj * HALF);
; #pragma unroll
;             for (int m = 0; m < 4; ++m) { const int row = row0 + ai * HALF + m * 16; bf16_t* rowp = xb + (size_t)row * ldc + col0;
;                 float ss = 0.f;
; #pragma unroll
;                 for (int bj = 0; bj < 2; ++bj) { const u32x4 w = b[m][bj];
;                     const f32x4 r0 = {__uint_as_float(w.x << 16), __uint_as_float(w.x & 0xffff0000u), __uint_as_float(w.y << 16), __uint_as_float(w.y & 0xffff0000u)};
;                     const f32x4 r1 = {__uint_as_float(w.z << 16), __uint_as_float(w.z & 0xffff0000u), __uint_as_float(w.w << 16), __uint_as_float(w.w & 0xffff0000u)};
;                     const f32x4 v0 = r0 + acc[ai][bj][m][0], v1 = r1 + acc[ai][bj][m][1];
;                     ss += ((v0[0] * v0[0] + v0[1] * v0[1]) + (v0[2] * v0[2] + v0[3] * v0[3])) + ((v1[0] * v1[0] + v1[1] * v1[1]) + (v1[2] * v1[2] + v1[3] * v1[3]));
;                     u32x4 o; o.x = cvt_pk_bf16(v0[0], v0[1]); o.y = cvt_pk_bf16(v0[2], v0[3]); o.z = cvt_pk_bf16(v1[0], v1[1]); o.w = cvt_pk_bf16(v1[2], v1[3]);
;                     *(u32x4*)(rowp + bj * HALF) = o; }
;                 ss += __shfl_xor(ss, 16); ss += __shfl_xor(ss, 32);
;                 if (fq == 0) rowss[(size_t)row * 32 + u.pn * 4 + wc] = ss; }
.LBB0_564:
	v_lshl_add_u32 v172, s42, 8, v186
	v_lshl_or_b32 v173, s41, 8, v188
	v_lshlrev_b32_e32 v173, 1, v173
	v_lshl_add_u32 v174, v172, 12, v173
	v_lshlrev_b32_e32 v175, 7, v172
	s_lshl_b32 s20, s41, 4
	s_lshl_b32 s21, s35, 2
	s_add_i32 s20, s20, s21
	v_add_u32_e32 v175, s20, v175
	global_load_dwordx4 v[130:133], v174, s[46:47]
	global_load_dwordx4 v[134:137], v174, s[46:47] offset:256
	v_add_u32_e32 v176, 0x10000, v174
	global_load_dwordx4 v[138:141], v176, s[46:47]
	global_load_dwordx4 v[142:145], v176, s[46:47] offset:256
	v_add_u32_e32 v176, 0x20000, v174
	global_load_dwordx4 v[146:149], v176, s[46:47]
	global_load_dwordx4 v[150:153], v176, s[46:47] offset:256
	v_add_u32_e32 v176, 0x30000, v174
	global_load_dwordx4 v[154:157], v176, s[46:47]
	global_load_dwordx4 v[158:161], v176, s[46:47] offset:256
	v_add_u32_e32 v176, 0x80000, v174
	global_load_dwordx4 v[196:199], v176, s[46:47]
	global_load_dwordx4 v[200:203], v176, s[46:47] offset:256
	v_add_u32_e32 v176, 0x90000, v174
	global_load_dwordx4 v[204:207], v176, s[46:47]
	global_load_dwordx4 v[208:211], v176, s[46:47] offset:256
	s_waitcnt vmcnt(10)
	v_lshlrev_b32_e32 v214, 16, v130
	v_and_b32_e32 v215, 0xffff0000, v130
	v_lshlrev_b32_e32 v216, 16, v131
	v_and_b32_e32 v217, 0xffff0000, v131
	v_lshlrev_b32_e32 v179, 16, v132
	v_and_b32_e32 v180, 0xffff0000, v132
	v_lshlrev_b32_e32 v181, 16, v133
	v_and_b32_e32 v182, 0xffff0000, v133
	v_add_f32_e32 v126, v126, v214
	v_add_f32_e32 v127, v127, v215
	v_add_f32_e32 v128, v128, v216
	v_add_f32_e32 v129, v129, v217
	v_add_f32_e32 v122, v122, v179
	v_add_f32_e32 v123, v123, v180
	v_add_f32_e32 v124, v124, v181
	v_add_f32_e32 v125, v125, v182
	v_mul_f32_e32 v214, v127, v127
	v_fmac_f32_e32 v214, v126, v126
	v_mul_f32_e32 v215, v129, v129
	v_fmac_f32_e32 v215, v128, v128
	v_add_f32_e32 v214, v214, v215
	v_mul_f32_e32 v215, v123, v123
	v_fmac_f32_e32 v215, v122, v122
	v_mul_f32_e32 v216, v125, v125
	v_fmac_f32_e32 v216, v124, v124
	v_add_f32_e32 v215, v215, v216
	v_add_f32_e32 v214, v214, v215
	v_mov_b32_e32 v183, v214
	v_cvt_pk_bf16_f32 v126, v126, v127
	v_cvt_pk_bf16_f32 v127, v128, v129
	v_cvt_pk_bf16_f32 v128, v122, v123
	v_cvt_pk_bf16_f32 v129, v124, v125
	v_lshlrev_b32_e32 v214, 16, v134
	v_and_b32_e32 v215, 0xffff0000, v134
	v_lshlrev_b32_e32 v216, 16, v135
	v_and_b32_e32 v217, 0xffff0000, v135
	v_lshlrev_b32_e32 v179, 16, v136
	v_and_b32_e32 v180, 0xffff0000, v136
	v_lshlrev_b32_e32 v181, 16, v137
	v_and_b32_e32 v182, 0xffff0000, v137
	v_add_f32_e32 v118, v118, v214
	v_add_f32_e32 v119, v119, v215
	v_add_f32_e32 v120, v120, v216
	v_add_f32_e32 v121, v121, v217
	v_add_f32_e32 v114, v114, v179
	v_add_f32_e32 v115, v115, v180
	v_add_f32_e32 v116, v116, v181
	v_add_f32_e32 v117, v117, v182
	v_mul_f32_e32 v214, v119, v119
	v_fmac_f32_e32 v214, v118, v118
	v_mul_f32_e32 v215, v121, v121
	v_fmac_f32_e32 v215, v120, v120
	v_add_f32_e32 v214, v214, v215
	v_mul_f32_e32 v215, v115, v115
	v_fmac_f32_e32 v215, v114, v114
	v_mul_f32_e32 v216, v117, v117
	v_fmac_f32_e32 v216, v116, v116
	v_add_f32_e32 v215, v215, v216
	v_add_f32_e32 v214, v214, v215
	v_add_f32_e32 v183, v183, v214
	v_cvt_pk_bf16_f32 v118, v118, v119
	v_cvt_pk_bf16_f32 v119, v120, v121
	v_cvt_pk_bf16_f32 v120, v114, v115
	v_cvt_pk_bf16_f32 v121, v116, v117
	v_add_u32_e32 v176, 0xa0000, v174
	global_load_dwordx4 v[130:133], v176, s[46:47]
	global_load_dwordx4 v[134:137], v176, s[46:47] offset:256
	global_store_dwordx4 v174, v[126:129], s[46:47]
	global_store_dwordx4 v174, v[118:121], s[46:47] offset:256
	v_mov_b32_e32 v217, v183
	s_nop 1
	v_permlane16_swap_b32_e32 v217, v183
	v_add_f32_e32 v183, v183, v217
	v_mov_b32_e32 v217, v183
	s_nop 1
	v_permlane32_swap_b32_e32 v217, v183
	v_add_f32_e32 v183, v183, v217
	s_and_saveexec_b64 s[22:23], s[0:1]
	global_store_dword v175, v183, s[8:9]
	s_or_b64 exec, exec, s[22:23]
	s_waitcnt vmcnt(13)
	v_add_u32_e32 v177, 0x10000, v174
	v_add_u32_e32 v178, 0x800, v175
	v_lshlrev_b32_e32 v214, 16, v138
	v_and_b32_e32 v215, 0xffff0000, v138
	v_lshlrev_b32_e32 v216, 16, v139
	v_and_b32_e32 v217, 0xffff0000, v139
	v_lshlrev_b32_e32 v179, 16, v140
	v_and_b32_e32 v180, 0xffff0000, v140
	v_lshlrev_b32_e32 v181, 16, v141
	v_and_b32_e32 v182, 0xffff0000, v141
	v_add_f32_e32 v110, v110, v214
	v_add_f32_e32 v111, v111, v215
	v_add_f32_e32 v112, v112, v216
	v_add_f32_e32 v113, v113, v217
	v_add_f32_e32 v106, v106, v179
	v_add_f32_e32 v107, v107, v180
	v_add_f32_e32 v108, v108, v181
	v_add_f32_e32 v109, v109, v182
	v_mul_f32_e32 v214, v111, v111
	v_fmac_f32_e32 v214, v110, v110
	v_mul_f32_e32 v215, v113, v113
	v_fmac_f32_e32 v215, v112, v112
	v_add_f32_e32 v214, v214, v215
	v_mul_f32_e32 v215, v107, v107
	v_fmac_f32_e32 v215, v106, v106
	v_mul_f32_e32 v216, v109, v109
	v_fmac_f32_e32 v216, v108, v108
	v_add_f32_e32 v215, v215, v216
	v_add_f32_e32 v214, v214, v215
	v_mov_b32_e32 v183, v214
	v_cvt_pk_bf16_f32 v110, v110, v111
	v_cvt_pk_bf16_f32 v111, v112, v113
	v_cvt_pk_bf16_f32 v112, v106, v107
	v_cvt_pk_bf16_f32 v113, v108, v109
	v_lshlrev_b32_e32 v214, 16, v142
	v_and_b32_e32 v215, 0xffff0000, v142
	v_lshlrev_b32_e32 v216, 16, v143
	v_and_b32_e32 v217, 0xffff0000, v143
	v_lshlrev_b32_e32 v179, 16, v144
	v_and_b32_e32 v180, 0xffff0000, v144
	v_lshlrev_b32_e32 v181, 16, v145
	v_and_b32_e32 v182, 0xffff0000, v145
	v_add_f32_e32 v102, v102, v214
	v_add_f32_e32 v103, v103, v215
	v_add_f32_e32 v104, v104, v216
	v_add_f32_e32 v105, v105, v217
	v_add_f32_e32 v98, v98, v179
	v_add_f32_e32 v99, v99, v180
	v_add_f32_e32 v100, v100, v181
	v_add_f32_e32 v101, v101, v182
	v_mul_f32_e32 v214, v103, v103
	v_fmac_f32_e32 v214, v102, v102
	v_mul_f32_e32 v215, v105, v105
	v_fmac_f32_e32 v215, v104, v104
	v_add_f32_e32 v214, v214, v215
	v_mul_f32_e32 v215, v99, v99
	v_fmac_f32_e32 v215, v98, v98
	v_mul_f32_e32 v216, v101, v101
	v_fmac_f32_e32 v216, v100, v100
	v_add_f32_e32 v215, v215, v216
	v_add_f32_e32 v214, v214, v215
	v_add_f32_e32 v183, v183, v214
	v_cvt_pk_bf16_f32 v102, v102, v103
	v_cvt_pk_bf16_f32 v103, v104, v105
	v_cvt_pk_bf16_f32 v104, v98, v99
	v_cvt_pk_bf16_f32 v105, v100, v101
	v_add_u32_e32 v176, 0xb0000, v174
	global_load_dwordx4 v[138:141], v176, s[46:47]
	global_load_dwordx4 v[142:145], v176, s[46:47] offset:256
	global_store_dwordx4 v177, v[110:113], s[46:47]
	global_store_dwordx4 v177, v[102:105], s[46:47] offset:256
	v_mov_b32_e32 v217, v183
	s_nop 1
	v_permlane16_swap_b32_e32 v217, v183
	v_add_f32_e32 v183, v183, v217
	v_mov_b32_e32 v217, v183
	s_nop 1
	v_permlane32_swap_b32_e32 v217, v183
	v_add_f32_e32 v183, v183, v217
	s_and_saveexec_b64 s[22:23], s[0:1]
	global_store_dword v178, v183, s[8:9]
	s_or_b64 exec, exec, s[22:23]
	s_waitcnt vmcnt(16)
; __device__ __forceinline__ unsigned cvt_pk_bf16(float lo, float hi) { f32x2 v = {lo, hi}; bf16x2_t b = __builtin_convertvector(v, bf16x2_t); return __builtin_bit_cast(unsigned, b); }
;     __device__ __forceinline__ void operator()(const f32x4 (&acc)[2][2][4][2], const Unit& u, int wr, int wc, int fr, int fq) const {
;     ...
;             for (int m = 0; m < 4; ++m) { const int row = row0 + ai * HALF + m * 16; bf16_t* rowp = xb + (size_t)row * ldc + col0;
;                 float ss = 0.f;
; #pragma unroll
;                 for (int bj = 0; bj < 2; ++bj) { const u32x4 w = b[m][bj];
;                     const f32x4 r0 = {__uint_as_float(w.x << 16), __uint_as_float(w.x & 0xffff0000u), __uint_as_float(w.y << 16), __uint_as_float(w.y & 0xffff0000u)};
;                     const f32x4 r1 = {__uint_as_float(w.z << 16), __uint_as_float(w.z & 0xffff0000u), __uint_as_float(w.w << 16), __uint_as_float(w.w & 0xffff0000u)};
;                     const f32x4 v0 = r0 + acc[ai][bj][m][0], v1 = r1 + acc[ai][bj][m][1];
;                     ss += ((v0[0] * v0[0] + v0[1] * v0[1]) + (v0[2] * v0[2] + v0[3] * v0[3])) + ((v1[0] * v1[0] + v1[1] * v1[1]) + (v1[2] * v1[2] + v1[3] * v1[3]));
;                     u32x4 o; o.x = cvt_pk_bf16(v0[0], v0[1]); o.y = cvt_pk_bf16(v0[2], v0[3]); o.z = cvt_pk_bf16(v1[0], v1[1]); o.w = cvt_pk_bf16(v1[2], v1[3]);
;                     *(u32x4*)(rowp + bj * HALF) = o; }
;                 ss += __shfl_xor(ss, 16); ss += __shfl_xor(ss, 32);
;                 if (fq == 0) rowss[(size_t)row * 32 + u.pn * 4 + wc] = ss; }
	v_add_u32_e32 v177, 0x20000, v174
	v_add_u32_e32 v178, 0x1000, v175
	v_lshlrev_b32_e32 v214, 16, v146
	v_and_b32_e32 v215, 0xffff0000, v146
	v_lshlrev_b32_e32 v216, 16, v147
	v_and_b32_e32 v217, 0xffff0000, v147
	v_lshlrev_b32_e32 v179, 16, v148
	v_and_b32_e32 v180, 0xffff0000, v148
	v_lshlrev_b32_e32 v181, 16, v149
	v_and_b32_e32 v182, 0xffff0000, v149
	v_add_f32_e32 v94, v94, v214
	v_add_f32_e32 v95, v95, v215
	v_add_f32_e32 v96, v96, v216
	v_add_f32_e32 v97, v97, v217
	v_add_f32_e32 v90, v90, v179
	v_add_f32_e32 v91, v91, v180
	v_add_f32_e32 v92, v92, v181
	v_add_f32_e32 v93, v93, v182
	v_mul_f32_e32 v214, v95, v95
	v_fmac_f32_e32 v214, v94, v94
	v_mul_f32_e32 v215, v97, v97
	v_fmac_f32_e32 v215, v96, v96
	v_add_f32_e32 v214, v214, v215
	v_mul_f32_e32 v215, v91, v91
	v_fmac_f32_e32 v215, v90, v90
	v_mul_f32_e32 v216, v93, v93
	v_fmac_f32_e32 v216, v92, v92
	v_add_f32_e32 v215, v215, v216
	v_add_f32_e32 v214, v214, v215
	v_mov_b32_e32 v183, v214
	v_cvt_pk_bf16_f32 v94, v94, v95
	v_cvt_pk_bf16_f32 v95, v96, v97
	v_cvt_pk_bf16_f32 v96, v90, v91
	v_cvt_pk_bf16_f32 v97, v92, v93
	v_lshlrev_b32_e32 v214, 16, v150
	v_and_b32_e32 v215, 0xffff0000, v150
	v_lshlrev_b32_e32 v216, 16, v151
	v_and_b32_e32 v217, 0xffff0000, v151
	v_lshlrev_b32_e32 v179, 16, v152
	v_and_b32_e32 v180, 0xffff0000, v152
	v_lshlrev_b32_e32 v181, 16, v153
	v_and_b32_e32 v182, 0xffff0000, v153
	v_add_f32_e32 v86, v86, v214
	v_add_f32_e32 v87, v87, v215
	v_add_f32_e32 v88, v88, v216
	v_add_f32_e32 v89, v89, v217
	v_add_f32_e32 v82, v82, v179
	v_add_f32_e32 v83, v83, v180
	v_add_f32_e32 v84, v84, v181
	v_add_f32_e32 v85, v85, v182
	v_mul_f32_e32 v214, v87, v87
	v_fmac_f32_e32 v214, v86, v86
	v_mul_f32_e32 v215, v89, v89
	v_fmac_f32_e32 v215, v88, v88
	v_add_f32_e32 v214, v214, v215
	v_mul_f32_e32 v215, v83, v83
	v_fmac_f32_e32 v215, v82, v82
	v_mul_f32_e32 v216, v85, v85
	v_fmac_f32_e32 v216, v84, v84
	v_add_f32_e32 v215, v215, v216
	v_add_f32_e32 v214, v214, v215
	v_add_f32_e32 v183, v183, v214
	v_cvt_pk_bf16_f32 v86, v86, v87
	v_cvt_pk_bf16_f32 v87, v88, v89
	v_cvt_pk_bf16_f32 v88, v82, v83
	v_cvt_pk_bf16_f32 v89, v84, v85
	global_store_dwordx4 v177, v[94:97], s[46:47]
	global_store_dwordx4 v177, v[86:89], s[46:47] offset:256
	v_mov_b32_e32 v217, v183
	s_nop 1
	v_permlane16_swap_b32_e32 v217, v183
	v_add_f32_e32 v183, v183, v217
	v_mov_b32_e32 v217, v183
	s_nop 1
	v_permlane32_swap_b32_e32 v217, v183
	v_add_f32_e32 v183, v183, v217
	s_and_saveexec_b64 s[22:23], s[0:1]
	global_store_dword v178, v183, s[8:9]
	s_or_b64 exec, exec, s[22:23]
	s_waitcnt vmcnt(17)
	v_add_u32_e32 v177, 0x30000, v174
	v_add_u32_e32 v178, 0x1800, v175
	v_lshlrev_b32_e32 v214, 16, v154
	v_and_b32_e32 v215, 0xffff0000, v154
	v_lshlrev_b32_e32 v216, 16, v155
	v_and_b32_e32 v217, 0xffff0000, v155
	v_lshlrev_b32_e32 v179, 16, v156
	v_and_b32_e32 v180, 0xffff0000, v156
	v_lshlrev_b32_e32 v181, 16, v157
	v_and_b32_e32 v182, 0xffff0000, v157
	v_add_f32_e32 v78, v78, v214
	v_add_f32_e32 v79, v79, v215
	v_add_f32_e32 v80, v80, v216
	v_add_f32_e32 v81, v81, v217
	v_add_f32_e32 v74, v74, v179
	v_add_f32_e32 v75, v75, v180
	v_add_f32_e32 v76, v76, v181
	v_add_f32_e32 v77, v77, v182
	v_mul_f32_e32 v214, v79, v79
	v_fmac_f32_e32 v214, v78, v78
	v_mul_f32_e32 v215, v81, v81
	v_fmac_f32_e32 v215, v80, v80
	v_add_f32_e32 v214, v214, v215
	v_mul_f32_e32 v215, v75, v75
	v_fmac_f32_e32 v215, v74, v74
	v_mul_f32_e32 v216, v77, v77
	v_fmac_f32_e32 v216, v76, v76
	v_add_f32_e32 v215, v215, v216
	v_add_f32_e32 v214, v214, v215
	v_mov_b32_e32 v183, v214
	v_cvt_pk_bf16_f32 v78, v78, v79
	v_cvt_pk_bf16_f32 v79, v80, v81
	v_cvt_pk_bf16_f32 v80, v74, v75
	v_cvt_pk_bf16_f32 v81, v76, v77
	v_lshlrev_b32_e32 v214, 16, v158
	v_and_b32_e32 v215, 0xffff0000, v158
	v_lshlrev_b32_e32 v216, 16, v159
	v_and_b32_e32 v217, 0xffff0000, v159
	v_lshlrev_b32_e32 v179, 16, v160
	v_and_b32_e32 v180, 0xffff0000, v160
	v_lshlrev_b32_e32 v181, 16, v161
	v_and_b32_e32 v182, 0xffff0000, v161
	v_add_f32_e32 v70, v70, v214
	v_add_f32_e32 v71, v71, v215
	v_add_f32_e32 v72, v72, v216
	v_add_f32_e32 v73, v73, v217
	v_add_f32_e32 v66, v66, v179
	v_add_f32_e32 v67, v67, v180
	v_add_f32_e32 v68, v68, v181
	v_add_f32_e32 v69, v69, v182
	v_mul_f32_e32 v214, v71, v71
	v_fmac_f32_e32 v214, v70, v70
	v_mul_f32_e32 v215, v73, v73
	v_fmac_f32_e32 v215, v72, v72
	v_add_f32_e32 v214, v214, v215
	v_mul_f32_e32 v215, v67, v67
	v_fmac_f32_e32 v215, v66, v66
	v_mul_f32_e32 v216, v69, v69
	v_fmac_f32_e32 v216, v68, v68
	v_add_f32_e32 v215, v215, v216
	v_add_f32_e32 v214, v214, v215
	v_add_f32_e32 v183, v183, v214
	v_cvt_pk_bf16_f32 v70, v70, v71
	v_cvt_pk_bf16_f32 v71, v72, v73
	v_cvt_pk_bf16_f32 v72, v66, v67
	v_cvt_pk_bf16_f32 v73, v68, v69
	global_store_dwordx4 v177, v[78:81], s[46:47]
	global_store_dwordx4 v177, v[70:73], s[46:47] offset:256
	v_mov_b32_e32 v217, v183
	s_nop 1
	v_permlane16_swap_b32_e32 v217, v183
	v_add_f32_e32 v183, v183, v217
	v_mov_b32_e32 v217, v183
	s_nop 1
	v_permlane32_swap_b32_e32 v217, v183
	v_add_f32_e32 v183, v183, v217
	s_and_saveexec_b64 s[22:23], s[0:1]
	global_store_dword v178, v183, s[8:9]
	s_or_b64 exec, exec, s[22:23]
	s_waitcnt vmcnt(18)
; __device__ __forceinline__ unsigned cvt_pk_bf16(float lo, float hi) { f32x2 v = {lo, hi}; bf16x2_t b = __builtin_convertvector(v, bf16x2_t); return __builtin_bit_cast(unsigned, b); }
;     __device__ __forceinline__ void operator()(const f32x4 (&acc)[2][2][4][2], const Unit& u, int wr, int wc, int fr, int fq) const {
;     ...
;             for (int m = 0; m < 4; ++m) { const int row = row0 + ai * HALF + m * 16; bf16_t* rowp = xb + (size_t)row * ldc + col0;
;                 float ss = 0.f;
; #pragma unroll
;                 for (int bj = 0; bj < 2; ++bj) { const u32x4 w = b[m][bj];
;                     const f32x4 r0 = {__uint_as_float(w.x << 16), __uint_as_float(w.x & 0xffff0000u), __uint_as_float(w.y << 16), __uint_as_float(w.y & 0xffff0000u)};
;                     const f32x4 r1 = {__uint_as_float(w.z << 16), __uint_as_float(w.z & 0xffff0000u), __uint_as_float(w.w << 16), __uint_as_float(w.w & 0xffff0000u)};
;                     const f32x4 v0 = r0 + acc[ai][bj][m][0], v1 = r1 + acc[ai][bj][m][1];
;                     ss += ((v0[0] * v0[0] + v0[1] * v0[1]) + (v0[2] * v0[2] + v0[3] * v0[3])) + ((v1[0] * v1[0] + v1[1] * v1[1]) + (v1[2] * v1[2] + v1[3] * v1[3]));
;                     u32x4 o; o.x = cvt_pk_bf16(v0[0], v0[1]); o.y = cvt_pk_bf16(v0[2], v0[3]); o.z = cvt_pk_bf16(v1[0], v1[1]); o.w = cvt_pk_bf16(v1[2], v1[3]);
;                     *(u32x4*)(rowp + bj * HALF) = o; }
;                 ss += __shfl_xor(ss, 16); ss += __shfl_xor(ss, 32);
;                 if (fq == 0) rowss[(size_t)row * 32 + u.pn * 4 + wc] = ss; }
	v_add_u32_e32 v177, 0x80000, v174
	v_add_u32_e32 v178, 0x4000, v175
	v_lshlrev_b32_e32 v214, 16, v196
	v_and_b32_e32 v215, 0xffff0000, v196
	v_lshlrev_b32_e32 v216, 16, v197
	v_and_b32_e32 v217, 0xffff0000, v197
	v_lshlrev_b32_e32 v179, 16, v198
	v_and_b32_e32 v180, 0xffff0000, v198
	v_lshlrev_b32_e32 v181, 16, v199
	v_and_b32_e32 v182, 0xffff0000, v199
	v_add_f32_e32 v62, v62, v214
	v_add_f32_e32 v63, v63, v215
	v_add_f32_e32 v64, v64, v216
	v_add_f32_e32 v65, v65, v217
	v_add_f32_e32 v58, v58, v179
	v_add_f32_e32 v59, v59, v180
	v_add_f32_e32 v60, v60, v181
	v_add_f32_e32 v61, v61, v182
	v_mul_f32_e32 v214, v63, v63
	v_fmac_f32_e32 v214, v62, v62
	v_mul_f32_e32 v215, v65, v65
	v_fmac_f32_e32 v215, v64, v64
	v_add_f32_e32 v214, v214, v215
	v_mul_f32_e32 v215, v59, v59
	v_fmac_f32_e32 v215, v58, v58
	v_mul_f32_e32 v216, v61, v61
	v_fmac_f32_e32 v216, v60, v60
	v_add_f32_e32 v215, v215, v216
	v_add_f32_e32 v214, v214, v215
	v_mov_b32_e32 v183, v214
	v_cvt_pk_bf16_f32 v62, v62, v63
	v_cvt_pk_bf16_f32 v63, v64, v65
	v_cvt_pk_bf16_f32 v64, v58, v59
	v_cvt_pk_bf16_f32 v65, v60, v61
	v_lshlrev_b32_e32 v214, 16, v200
	v_and_b32_e32 v215, 0xffff0000, v200
	v_lshlrev_b32_e32 v216, 16, v201
	v_and_b32_e32 v217, 0xffff0000, v201
	v_lshlrev_b32_e32 v179, 16, v202
	v_and_b32_e32 v180, 0xffff0000, v202
	v_lshlrev_b32_e32 v181, 16, v203
	v_and_b32_e32 v182, 0xffff0000, v203
	v_add_f32_e32 v54, v54, v214
	v_add_f32_e32 v55, v55, v215
	v_add_f32_e32 v56, v56, v216
	v_add_f32_e32 v57, v57, v217
	v_add_f32_e32 v50, v50, v179
	v_add_f32_e32 v51, v51, v180
	v_add_f32_e32 v52, v52, v181
	v_add_f32_e32 v53, v53, v182
	v_mul_f32_e32 v214, v55, v55
	v_fmac_f32_e32 v214, v54, v54
	v_mul_f32_e32 v215, v57, v57
	v_fmac_f32_e32 v215, v56, v56
	v_add_f32_e32 v214, v214, v215
	v_mul_f32_e32 v215, v51, v51
	v_fmac_f32_e32 v215, v50, v50
	v_mul_f32_e32 v216, v53, v53
	v_fmac_f32_e32 v216, v52, v52
	v_add_f32_e32 v215, v215, v216
	v_add_f32_e32 v214, v214, v215
	v_add_f32_e32 v183, v183, v214
	v_cvt_pk_bf16_f32 v54, v54, v55
	v_cvt_pk_bf16_f32 v55, v56, v57
	v_cvt_pk_bf16_f32 v56, v50, v51
	v_cvt_pk_bf16_f32 v57, v52, v53
	global_store_dwordx4 v177, v[62:65], s[46:47]
	global_store_dwordx4 v177, v[54:57], s[46:47] offset:256
	v_mov_b32_e32 v217, v183
	s_nop 1
	v_permlane16_swap_b32_e32 v217, v183
	v_add_f32_e32 v183, v183, v217
	v_mov_b32_e32 v217, v183
	s_nop 1
	v_permlane32_swap_b32_e32 v217, v183
	v_add_f32_e32 v183, v183, v217
	s_and_saveexec_b64 s[22:23], s[0:1]
	global_store_dword v178, v183, s[8:9]
	s_or_b64 exec, exec, s[22:23]
	s_waitcnt vmcnt(19)
	v_add_u32_e32 v177, 0x90000, v174
	v_add_u32_e32 v178, 0x4800, v175
	v_lshlrev_b32_e32 v214, 16, v204
	v_and_b32_e32 v215, 0xffff0000, v204
	v_lshlrev_b32_e32 v216, 16, v205
	v_and_b32_e32 v217, 0xffff0000, v205
	v_lshlrev_b32_e32 v179, 16, v206
	v_and_b32_e32 v180, 0xffff0000, v206
	v_lshlrev_b32_e32 v181, 16, v207
	v_and_b32_e32 v182, 0xffff0000, v207
	v_add_f32_e32 v46, v46, v214
	v_add_f32_e32 v47, v47, v215
	v_add_f32_e32 v48, v48, v216
	v_add_f32_e32 v49, v49, v217
	v_add_f32_e32 v42, v42, v179
	v_add_f32_e32 v43, v43, v180
	v_add_f32_e32 v44, v44, v181
	v_add_f32_e32 v45, v45, v182
	v_mul_f32_e32 v214, v47, v47
	v_fmac_f32_e32 v214, v46, v46
	v_mul_f32_e32 v215, v49, v49
	v_fmac_f32_e32 v215, v48, v48
	v_add_f32_e32 v214, v214, v215
	v_mul_f32_e32 v215, v43, v43
	v_fmac_f32_e32 v215, v42, v42
	v_mul_f32_e32 v216, v45, v45
	v_fmac_f32_e32 v216, v44, v44
	v_add_f32_e32 v215, v215, v216
	v_add_f32_e32 v214, v214, v215
	v_mov_b32_e32 v183, v214
	v_cvt_pk_bf16_f32 v46, v46, v47
	v_cvt_pk_bf16_f32 v47, v48, v49
	v_cvt_pk_bf16_f32 v48, v42, v43
	v_cvt_pk_bf16_f32 v49, v44, v45
	v_lshlrev_b32_e32 v214, 16, v208
	v_and_b32_e32 v215, 0xffff0000, v208
	v_lshlrev_b32_e32 v216, 16, v209
	v_and_b32_e32 v217, 0xffff0000, v209
	v_lshlrev_b32_e32 v179, 16, v210
	v_and_b32_e32 v180, 0xffff0000, v210
	v_lshlrev_b32_e32 v181, 16, v211
	v_and_b32_e32 v182, 0xffff0000, v211
	v_add_f32_e32 v38, v38, v214
	v_add_f32_e32 v39, v39, v215
	v_add_f32_e32 v40, v40, v216
	v_add_f32_e32 v41, v41, v217
	v_add_f32_e32 v34, v34, v179
	v_add_f32_e32 v35, v35, v180
	v_add_f32_e32 v36, v36, v181
	v_add_f32_e32 v37, v37, v182
	v_mul_f32_e32 v214, v39, v39
	v_fmac_f32_e32 v214, v38, v38
	v_mul_f32_e32 v215, v41, v41
	v_fmac_f32_e32 v215, v40, v40
	v_add_f32_e32 v214, v214, v215
	v_mul_f32_e32 v215, v35, v35
	v_fmac_f32_e32 v215, v34, v34
	v_mul_f32_e32 v216, v37, v37
	v_fmac_f32_e32 v216, v36, v36
	v_add_f32_e32 v215, v215, v216
	v_add_f32_e32 v214, v214, v215
	v_add_f32_e32 v183, v183, v214
	v_cvt_pk_bf16_f32 v38, v38, v39
	v_cvt_pk_bf16_f32 v39, v40, v41
	v_cvt_pk_bf16_f32 v40, v34, v35
	v_cvt_pk_bf16_f32 v41, v36, v37
	global_store_dwordx4 v177, v[46:49], s[46:47]
	global_store_dwordx4 v177, v[38:41], s[46:47] offset:256
	v_mov_b32_e32 v217, v183
	s_nop 1
	v_permlane16_swap_b32_e32 v217, v183
	v_add_f32_e32 v183, v183, v217
	v_mov_b32_e32 v217, v183
	s_nop 1
	v_permlane32_swap_b32_e32 v217, v183
	v_add_f32_e32 v183, v183, v217
	s_and_saveexec_b64 s[22:23], s[0:1]
	global_store_dword v178, v183, s[8:9]
	s_or_b64 exec, exec, s[22:23]
	s_waitcnt vmcnt(20)
; __device__ __forceinline__ unsigned cvt_pk_bf16(float lo, float hi) { f32x2 v = {lo, hi}; bf16x2_t b = __builtin_convertvector(v, bf16x2_t); return __builtin_bit_cast(unsigned, b); }
; #define PG8_BAR __builtin_amdgcn_s_barrier()
;     __device__ __forceinline__ void operator()(const f32x4 (&acc)[2][2][4][2], const Unit& u, int wr, int wc, int fr, int fq) const {
;     ...
;             for (int m = 0; m < 4; ++m) { const int row = row0 + ai * HALF + m * 16; bf16_t* rowp = xb + (size_t)row * ldc + col0;
;                 float ss = 0.f;
; #pragma unroll
;                 for (int bj = 0; bj < 2; ++bj) { const u32x4 w = b[m][bj];
;                     const f32x4 r0 = {__uint_as_float(w.x << 16), __uint_as_float(w.x & 0xffff0000u), __uint_as_float(w.y << 16), __uint_as_float(w.y & 0xffff0000u)};
;                     const f32x4 r1 = {__uint_as_float(w.z << 16), __uint_as_float(w.z & 0xffff0000u), __uint_as_float(w.w << 16), __uint_as_float(w.w & 0xffff0000u)};
;                     const f32x4 v0 = r0 + acc[ai][bj][m][0], v1 = r1 + acc[ai][bj][m][1];
;                     ss += ((v0[0] * v0[0] + v0[1] * v0[1]) + (v0[2] * v0[2] + v0[3] * v0[3])) + ((v1[0] * v1[0] + v1[1] * v1[1]) + (v1[2] * v1[2] + v1[3] * v1[3]));
;                     u32x4 o; o.x = cvt_pk_bf16(v0[0], v0[1]); o.y = cvt_pk_bf16(v0[2], v0[3]); o.z = cvt_pk_bf16(v1[0], v1[1]); o.w = cvt_pk_bf16(v1[2], v1[3]);
;                     *(u32x4*)(rowp + bj * HALF) = o; }
;                 ss += __shfl_xor(ss, 16); ss += __shfl_xor(ss, 32);
;                 if (fq == 0) rowss[(size_t)row * 32 + u.pn * 4 + wc] = ss; }
; template <class Epi, class Sched, bool ALIGN_EPI = false, bool SP2 = false>
; __device__ __forceinline__ void gemm_phase(PG8_LAS unsigned char* lds, const Gemm g, const Sched& S, const Epi& E, const int wave_s) {
;     ...
;         if constexpr (!Epi::AFTER_DRAIN) { E(acc, cur, wr, wc, fr, fq); S.done(cur); }
;         if (!has_next) break;
; #pragma unroll
;         for (int a = 0; a < 2; ++a)
; #pragma unroll
;             for (int b = 0; b < 2; ++b)
; #pragma unroll
;                 for (int m = 0; m < 4; ++m)
; #pragma unroll
;                     for (int n = 0; n < 2; ++n) acc[a][b][m][n] = (f32x4){0.f, 0.f, 0.f, 0.f};
;         cur = nxt; cA = nA; cB = nB; ++ui;
;         if constexpr (ALIGN_EPI) { if (wr == 1) PG8_BAR; }
;     }
	v_add_u32_e32 v177, 0xa0000, v174
	v_add_u32_e32 v178, 0x5000, v175
	v_lshlrev_b32_e32 v214, 16, v130
	v_and_b32_e32 v215, 0xffff0000, v130
	v_lshlrev_b32_e32 v216, 16, v131
	v_and_b32_e32 v217, 0xffff0000, v131
	v_lshlrev_b32_e32 v179, 16, v132
	v_and_b32_e32 v180, 0xffff0000, v132
	v_lshlrev_b32_e32 v181, 16, v133
	v_and_b32_e32 v182, 0xffff0000, v133
	v_add_f32_e32 v30, v30, v214
	v_add_f32_e32 v31, v31, v215
	v_add_f32_e32 v32, v32, v216
	v_add_f32_e32 v33, v33, v217
	v_add_f32_e32 v26, v26, v179
	v_add_f32_e32 v27, v27, v180
	v_add_f32_e32 v28, v28, v181
	v_add_f32_e32 v29, v29, v182
	v_mul_f32_e32 v214, v31, v31
	v_fmac_f32_e32 v214, v30, v30
	v_mul_f32_e32 v215, v33, v33
	v_fmac_f32_e32 v215, v32, v32
	v_add_f32_e32 v214, v214, v215
	v_mul_f32_e32 v215, v27, v27
	v_fmac_f32_e32 v215, v26, v26
	v_mul_f32_e32 v216, v29, v29
	v_fmac_f32_e32 v216, v28, v28
	v_add_f32_e32 v215, v215, v216
	v_add_f32_e32 v214, v214, v215
	v_mov_b32_e32 v183, v214
	v_cvt_pk_bf16_f32 v30, v30, v31
	v_cvt_pk_bf16_f32 v31, v32, v33
	v_cvt_pk_bf16_f32 v32, v26, v27
	v_cvt_pk_bf16_f32 v33, v28, v29
	v_lshlrev_b32_e32 v214, 16, v134
	v_and_b32_e32 v215, 0xffff0000, v134
	v_lshlrev_b32_e32 v216, 16, v135
	v_and_b32_e32 v217, 0xffff0000, v135
	v_lshlrev_b32_e32 v179, 16, v136
	v_and_b32_e32 v180, 0xffff0000, v136
	v_lshlrev_b32_e32 v181, 16, v137
	v_and_b32_e32 v182, 0xffff0000, v137
	v_add_f32_e32 v22, v22, v214
	v_add_f32_e32 v23, v23, v215
	v_add_f32_e32 v24, v24, v216
	v_add_f32_e32 v25, v25, v217
	v_add_f32_e32 v18, v18, v179
	v_add_f32_e32 v19, v19, v180
	v_add_f32_e32 v20, v20, v181
	v_add_f32_e32 v21, v21, v182
	v_mul_f32_e32 v214, v23, v23
	v_fmac_f32_e32 v214, v22, v22
	v_mul_f32_e32 v215, v25, v25
	v_fmac_f32_e32 v215, v24, v24
	v_add_f32_e32 v214, v214, v215
	v_mul_f32_e32 v215, v19, v19
	v_fmac_f32_e32 v215, v18, v18
	v_mul_f32_e32 v216, v21, v21
	v_fmac_f32_e32 v216, v20, v20
	v_add_f32_e32 v215, v215, v216
	v_add_f32_e32 v214, v214, v215
	v_add_f32_e32 v183, v183, v214
	v_cvt_pk_bf16_f32 v22, v22, v23
	v_cvt_pk_bf16_f32 v23, v24, v25
	v_cvt_pk_bf16_f32 v24, v18, v19
	v_cvt_pk_bf16_f32 v25, v20, v21
	global_store_dwordx4 v177, v[30:33], s[46:47]
	global_store_dwordx4 v177, v[22:25], s[46:47] offset:256
	v_mov_b32_e32 v217, v183
	s_nop 1
	v_permlane16_swap_b32_e32 v217, v183
	v_add_f32_e32 v183, v183, v217
	v_mov_b32_e32 v217, v183
	s_nop 1
	v_permlane32_swap_b32_e32 v217, v183
	v_add_f32_e32 v183, v183, v217
	s_and_saveexec_b64 s[22:23], s[0:1]
	global_store_dword v178, v183, s[8:9]
	s_or_b64 exec, exec, s[22:23]
	s_waitcnt vmcnt(18)
	v_add_u32_e32 v177, 0xb0000, v174
	v_add_u32_e32 v178, 0x5800, v175
	v_lshlrev_b32_e32 v214, 16, v138
	v_and_b32_e32 v215, 0xffff0000, v138
	v_lshlrev_b32_e32 v216, 16, v139
	v_and_b32_e32 v217, 0xffff0000, v139
	v_lshlrev_b32_e32 v179, 16, v140
	v_and_b32_e32 v180, 0xffff0000, v140
	v_lshlrev_b32_e32 v181, 16, v141
	v_and_b32_e32 v182, 0xffff0000, v141
	v_add_f32_e32 v14, v14, v214
	v_add_f32_e32 v15, v15, v215
	v_add_f32_e32 v16, v16, v216
	v_add_f32_e32 v17, v17, v217
	v_add_f32_e32 v10, v10, v179
	v_add_f32_e32 v11, v11, v180
	v_add_f32_e32 v12, v12, v181
	v_add_f32_e32 v13, v13, v182
	v_mul_f32_e32 v214, v15, v15
	v_fmac_f32_e32 v214, v14, v14
	v_mul_f32_e32 v215, v17, v17
	v_fmac_f32_e32 v215, v16, v16
	v_add_f32_e32 v214, v214, v215
	v_mul_f32_e32 v215, v11, v11
	v_fmac_f32_e32 v215, v10, v10
	v_mul_f32_e32 v216, v13, v13
	v_fmac_f32_e32 v216, v12, v12
	v_add_f32_e32 v215, v215, v216
	v_add_f32_e32 v214, v214, v215
	v_mov_b32_e32 v183, v214
	v_cvt_pk_bf16_f32 v14, v14, v15
	v_cvt_pk_bf16_f32 v15, v16, v17
	v_cvt_pk_bf16_f32 v16, v10, v11
	v_cvt_pk_bf16_f32 v17, v12, v13
	v_lshlrev_b32_e32 v214, 16, v142
	v_and_b32_e32 v215, 0xffff0000, v142
	v_lshlrev_b32_e32 v216, 16, v143
	v_and_b32_e32 v217, 0xffff0000, v143
	v_lshlrev_b32_e32 v179, 16, v144
	v_and_b32_e32 v180, 0xffff0000, v144
	v_lshlrev_b32_e32 v181, 16, v145
	v_and_b32_e32 v182, 0xffff0000, v145
	v_add_f32_e32 v6, v6, v214
	v_add_f32_e32 v7, v7, v215
	v_add_f32_e32 v8, v8, v216
	v_add_f32_e32 v9, v9, v217
	v_add_f32_e32 v2, v2, v179
	v_add_f32_e32 v3, v3, v180
	v_add_f32_e32 v4, v4, v181
	v_add_f32_e32 v5, v5, v182
	v_mul_f32_e32 v214, v7, v7
	v_fmac_f32_e32 v214, v6, v6
	v_mul_f32_e32 v215, v9, v9
	v_fmac_f32_e32 v215, v8, v8
	v_add_f32_e32 v214, v214, v215
	v_mul_f32_e32 v215, v3, v3
	v_fmac_f32_e32 v215, v2, v2
	v_mul_f32_e32 v216, v5, v5
	v_fmac_f32_e32 v216, v4, v4
	v_add_f32_e32 v215, v215, v216
	v_add_f32_e32 v214, v214, v215
	v_add_f32_e32 v183, v183, v214
	v_cvt_pk_bf16_f32 v6, v6, v7
	v_cvt_pk_bf16_f32 v7, v8, v9
	v_cvt_pk_bf16_f32 v8, v2, v3
	v_cvt_pk_bf16_f32 v9, v4, v5
	global_store_dwordx4 v177, v[14:17], s[46:47]
	global_store_dwordx4 v177, v[6:9], s[46:47] offset:256
	v_mov_b32_e32 v217, v183
	s_nop 1
	v_permlane16_swap_b32_e32 v217, v183
	v_add_f32_e32 v183, v183, v217
	v_mov_b32_e32 v217, v183
	s_nop 1
	v_permlane32_swap_b32_e32 v217, v183
	v_add_f32_e32 v183, v183, v217
	s_and_saveexec_b64 s[22:23], s[0:1]
	global_store_dword v178, v183, s[8:9]
	s_or_b64 exec, exec, s[22:23]
	s_andn2_b64 vcc, exec, s[4:5]
	s_mov_b64 s[4:5], -1
	s_cbranch_vccnz .LBB0_553
	s_andn2_b64 vcc, exec, s[6:7]
	s_cbranch_vccnz .LBB0_552
	s_barrier
	s_branch .LBB0_552
